# adds: per-unit store drain moved out of the stick-breaking unit loop; HGRN prep reads raw bf16 halves with d16_hi LDS loads
# speedup vs baseline: 1.0114x; 1.0063x over previous
; __global__ void __launch_bounds__(NTHREADS, 2) fwd_megakernel(Params Pkern) {
;     ...
;             if (PM(16)) { SETUP if (DUPMASK & 4) for (int u = gw; u < NBATCH * 8 * 64; u += NGW) sb_unit<true>(u >> 9, (u >> 6) & 7, u & 63, PB, SBVT);
;               for (int u = gw; u < NBATCH * 8 * 64; u += NGW) sb_unit<false>(u >> 9, (u >> 6) & 7, u & 63, PB, SBVT); }
.LBB0_739:
	v_mov_b32_e32 v0, v234
	s_movk_i32 s6, 0x2000
	v_ashrrev_i32_e32 v1, 6, v0
	v_add_u32_e32 v3, s93, v1
	v_cmp_gt_i32_e32 vcc, s6, v3
	s_mov_b64 s[6:7], exec
	v_writelane_b32 v252, s6, 51
	s_nop 1
	v_writelane_b32 v252, s7, 52
	s_and_b64 s[6:7], s[6:7], vcc
	s_mov_b64 exec, s[6:7]
	s_cbranch_execz .LBB0_744
	s_load_dwordx2 s[4:5], s[90:91], 0xd0
	v_lshrrev_b32_e32 v0, 6, v0
	v_readlane_b32 s6, v252, 41
	s_mov_b64 s[40:41], 0
	s_waitcnt lgkmcnt(0)
	s_add_u32 s42, s4, 0x8100000
	s_addc_u32 s43, s5, 0
	s_add_u32 s38, s4, 0x1db80000
	v_add_u16_e32 v87, s6, v0
	s_addc_u32 s39, s5, 0
	s_waitcnt vmcnt(0)
; __device__ __forceinline__ int otid() { int t = threadIdx.x; asm volatile("" : "+v"(t)); return t; }
; __device__ __forceinline__ void sb_load(SbFrags& F, const bf16_t* Pm, const bf16_t* VT, size_t tok0, int kv0, int h, int r32, int hi) {
;     const bf16_t* krow = Pm + (tok0 + kv0 + r32) * PW + PC_SBK + h * 64;
; #pragma unroll
;     for (int s = 0; s < 4; ++s) F.kf[s] = *(const bf16x8*)(krow + 16 * s + 8 * hi);
; #pragma unroll
;     for (int s = 0; s < 2; ++s) {
;         const bf16_t* v0p = VT + (size_t)(h * 64 + r32) * VTLD + tok0 + kv0 + 16 * s + 4 * hi; const bf16_t* v1p = v0p + (size_t)32 * VTLD;
;         F.v[4 * s + 0] = *(const s16x4*)v0p; F.v[4 * s + 1] = *(const s16x4*)(v0p + 8); F.v[4 * s + 2] = *(const s16x4*)v1p; F.v[4 * s + 3] = *(const s16x4*)(v1p + 8);
;     }
; }
; template <bool DRY> __device__ __forceinline__ void sb_unit(int b, int h, int qi, bf16_t* Pm, const bf16_t* VT) {
;     const int lane = otid() & 63, r32 = lane & 31, hi = lane >> 5;
;     const size_t tok0 = (size_t)b * SEQ; const int q0 = qi * 32;
;     bf16_t* qrow = Pm + (tok0 + q0 + r32) * PW + PC_SBQ + h * 64;
;     bf16x8 qf[4];
; #pragma unroll
;     for (int s = 0; s < 4; ++s) qf[s] = *(const bf16x8*)(qrow + 16 * s + 8 * hi);
;     float R = 0.f; f32x16 o0 = {}, o1 = {};
;     SbFrags cur, nxt;
;     sb_load(cur, Pm, VT, tok0, qi * 32, h, r32, hi);
; #pragma unroll 1
;     ...
;         sb_load(nxt, Pm, VT, tok0, (kt > 0 ? kt - 1 : 0) * 32, h, r32, hi);
.LBB0_741:
	v_ashrrev_i32_e32 v4, 9, v3
	v_mov_b32_e32 v0, v234
	v_and_b32_e32 v100, 63, v3
	v_ashrrev_i32_e32 v5, 31, v4
	v_and_b32_e32 v15, 31, v0
	v_bfe_u32 v16, v0, 5, 1
	v_lshlrev_b64 v[0:1], 11, v[4:5]
	v_lshlrev_b32_e32 v17, 5, v100
	v_or3_b32 v8, v15, v17, v0
	v_mov_b64_e32 v[6:7], s[42:43]
	v_and_b32_e32 v14, 0x1c0, v3
	v_mad_u64_u32 v[6:7], s[4:5], v8, s24, v[6:7]
	v_mad_i32_i24 v7, v1, s24, v7
	v_lshlrev_b32_e32 v8, 1, v14
	v_mov_b32_e32 v9, v2
	v_lshl_add_u64 v[84:85], v[6:7], 0, v[8:9]
	v_lshlrev_b32_e32 v10, 4, v16
	v_mov_b32_e32 v11, v2
	v_lshl_add_u64 v[12:13], v[84:85], 0, v[10:11]
	global_load_dwordx4 v[52:55], v[12:13], off offset:1280
	global_load_dwordx4 v[56:59], v[12:13], off offset:1312
	global_load_dwordx4 v[60:63], v[12:13], off offset:1344
	global_load_dwordx4 v[64:67], v[12:13], off offset:1376
	v_or_b32_e32 v12, v15, v14
	v_mul_u32_u24_e32 v12, 0x8200, v12
	v_lshlrev_b32_e32 v12, 1, v12
	v_mov_b32_e32 v13, v2
	v_lshl_add_u64 v[12:13], s[38:39], 0, v[12:13]
	v_lshlrev_b64 v[4:5], 12, v[4:5]
	v_lshlrev_b32_e32 v6, 3, v16
	v_mov_b32_e32 v7, v2
	v_lshl_add_u64 v[4:5], v[12:13], 0, v[4:5]
	v_lshlrev_b32_e32 v12, 6, v100
	v_mov_b32_e32 v13, v2
	v_lshl_add_u64 v[12:13], v[4:5], 0, v[12:13]
	v_lshl_add_u64 v[88:89], v[4:5], 0, v[6:7]
	v_xor_b32_e32 v4, 32, v238
	v_add_u32_e32 v5, 64, v239
	v_cmp_lt_i32_e32 vcc, v4, v5
	v_lshlrev_b32_e32 v86, 2, v16
	v_and_b32_e32 v98, 63, v87
	v_cndmask_b32_e32 v4, v238, v4, vcc
	v_lshlrev_b32_e32 v101, 2, v4
	v_or_b32_e32 v4, 1, v86
	v_cmp_lt_u32_e64 s[46:47], v4, v15
	v_or_b32_e32 v4, 2, v86
	v_cmp_lt_u32_e64 s[48:49], v4, v15
	v_or_b32_e32 v4, 3, v86
	v_cmp_lt_u32_e64 s[50:51], v4, v15
	v_or_b32_e32 v4, 8, v86
	v_cmp_lt_u32_e64 s[52:53], v4, v15
	v_or_b32_e32 v4, 9, v86
	v_cmp_lt_u32_e64 s[54:55], v4, v15
	v_or_b32_e32 v4, 10, v86
	v_cmp_lt_u32_e64 s[56:57], v4, v15
	v_or_b32_e32 v4, 11, v86
	v_cmp_lt_u32_e64 s[58:59], v4, v15
	v_or_b32_e32 v4, 16, v86
	v_cmp_lt_u32_e64 s[60:61], v4, v15
	v_or_b32_e32 v4, 17, v86
	v_cmp_lt_u32_e64 s[62:63], v4, v15
	v_or_b32_e32 v4, 18, v86
	v_cmp_lt_u32_e64 s[64:65], v4, v15
	v_or_b32_e32 v4, 19, v86
	v_cmp_lt_u32_e64 s[66:67], v4, v15
	v_or_b32_e32 v4, 24, v86
	v_cmp_lt_u32_e64 s[68:69], v4, v15
	v_or_b32_e32 v4, 25, v86
	v_cmp_lt_u32_e64 s[70:71], v4, v15
	v_or_b32_e32 v4, 26, v86
	v_cmp_lt_u32_e64 s[72:73], v4, v15
	v_or_b32_e32 v4, 27, v86
	v_or_b32_e32 v0, v0, v15
	v_cmp_lt_u32_e64 s[74:75], v4, v15
	v_lshl_add_u64 v[4:5], s[42:43], 0, v[8:9]
	v_mov_b32_e32 v102, 0
	v_lshlrev_b32_e32 v99, 5, v98
	v_or_b32_e32 v90, v0, v17
	v_mov_b32_e32 v91, v1
	v_lshl_add_u64 v[94:95], v[12:13], 0, v[6:7]
	s_mov_b32 s28, 0
	v_cmp_eq_u32_e64 s[12:13], 0, v16
	v_cmp_lt_u32_e64 s[44:45], v86, v15
	v_lshl_add_u64 v[92:93], v[4:5], 0, v[10:11]
	s_mov_b64 s[34:35], 0
	v_mov_b32_e32 v4, 0
	v_mov_b32_e32 v5, v102
	v_mov_b32_e32 v6, v102
	v_mov_b32_e32 v7, v102
	v_mov_b32_e32 v8, v102
	v_mov_b32_e32 v9, v102
	v_mov_b32_e32 v10, v102
	v_mov_b32_e32 v11, v102
	v_mov_b32_e32 v12, v102
	v_mov_b32_e32 v13, v102
	v_mov_b32_e32 v14, v102
	v_mov_b32_e32 v15, v102
	v_mov_b32_e32 v16, v102
	v_mov_b32_e32 v17, v102
	v_mov_b32_e32 v18, v102
	v_mov_b32_e32 v19, v102
	v_mov_b32_e32 v20, 0
	v_mov_b32_e32 v21, v102
	v_mov_b32_e32 v22, v102
	v_mov_b32_e32 v23, v102
	v_mov_b32_e32 v24, v102
	v_mov_b32_e32 v25, v102
	v_mov_b32_e32 v26, v102
	v_mov_b32_e32 v27, v102
	v_mov_b32_e32 v28, v102
	v_mov_b32_e32 v29, v102
	v_mov_b32_e32 v30, v102
	v_mov_b32_e32 v31, v102
	v_mov_b32_e32 v32, v102
	v_mov_b32_e32 v33, v102
	v_mov_b32_e32 v34, v102
	v_mov_b32_e32 v35, v102
	v_readfirstlane_b32 s14, v234
	s_lshl_b32 s98, s14, 8
	v_and_b32_e32 v36, 63, v234
	v_lshrrev_b32_e32 v37, 3, v36
	v_and_b32_e32 v38, 7, v36
	v_xor_b32_e32 v38, v38, v37
	v_ashrrev_i32_e32 v40, 9, v3
	v_lshlrev_b32_e32 v40, 11, v40
	v_and_b32_e32 v41, 63, v3
	v_lshl_add_u32 v40, v41, 5, v40
	v_bfe_u32 v42, v3, 6, 3
	v_add_u32_e32 v39, v40, v37
	v_lshlrev_b32_e32 v44, 7, v42
	v_lshl_add_u32 v44, v38, 4, v44
	v_add_u32_e32 v44, 0x900, v44
	v_mov_b32_e32 v45, 0
	v_mov_b64_e32 v[172:173], s[42:43]
	v_mad_u64_u32 v[172:173], vcc, v39, s24, v[172:173]
	v_lshl_add_u64 v[172:173], v[172:173], 0, v[44:45]
	v_mov_b32_e32 v46, 0xea00
	v_mov_b32_e32 v47, 0
	v_lshl_add_u64 v[174:175], v[172:173], 0, v[46:47]
	v_lshl_add_u64 v[176:177], v[174:175], 0, v[46:47]
	v_lshl_add_u64 v[178:179], v[176:177], 0, v[46:47]
	v_lshrrev_b32_e32 v37, 2, v36
	v_and_b32_e32 v38, 3, v36
	v_bfe_u32 v49, v36, 4, 2
	v_xor_b32_e32 v38, v38, v49
	v_lshl_add_u32 v39, v42, 6, v37
	v_lshlrev_b32_e32 v44, 1, v40
	v_lshl_add_u32 v44, v38, 4, v44
	v_mov_b64_e32 v[180:181], s[38:39]
	v_mov_b32_e32 v49, 0x10400
	v_mad_u64_u32 v[180:181], vcc, v39, v49, v[180:181]
	v_lshl_add_u64 v[180:181], v[180:181], 0, v[44:45]
	v_mov_b32_e32 v46, 0x104000
	v_lshl_add_u64 v[182:183], v[180:181], 0, v[46:47]
	v_lshl_add_u64 v[184:185], v[182:183], 0, v[46:47]
	v_lshl_add_u64 v[186:187], v[184:185], 0, v[46:47]
	v_mov_b32_e32 v188, 0xfffc5800
	v_mov_b32_e32 v189, -1
	v_mov_b32_e32 v190, 0xffffffc0
	v_mov_b32_e32 v191, -1
	v_and_b32_e32 v37, 31, v234
	v_bfe_u32 v38, v234, 5, 1
	v_and_b32_e32 v39, 7, v37
	v_lshlrev_b32_e32 v44, 7, v37
	v_add_u32_e32 v49, 0, v38
	v_xor_b32_e32 v49, v49, v39
	v_lshl_add_u32 v192, v49, 4, v44
	v_add_u32_e32 v49, 2, v38
	v_xor_b32_e32 v49, v49, v39
	v_lshl_add_u32 v193, v49, 4, v44
	v_add_u32_e32 v49, 4, v38
	v_xor_b32_e32 v49, v49, v39
	v_lshl_add_u32 v194, v49, 4, v44
	v_add_u32_e32 v49, 6, v38
	v_xor_b32_e32 v49, v49, v39
	v_lshl_add_u32 v195, v49, 4, v44
	v_bfe_u32 v39, v37, 2, 2
	v_lshlrev_b32_e32 v44, 6, v37
	v_lshl_add_u32 v44, v38, 3, v44
	v_xor_b32_e32 v49, 0, v39
	v_lshl_add_u32 v196, v49, 4, v44
	v_xor_b32_e32 v49, 1, v39
	v_lshl_add_u32 v197, v49, 4, v44
	v_xor_b32_e32 v49, 2, v39
	v_lshl_add_u32 v198, v49, 4, v44
	v_xor_b32_e32 v49, 3, v39
	v_lshl_add_u32 v199, v49, 4, v44
	s_add_i32 m0, s98, 0
	s_nop 0
	global_load_lds_dwordx4 v[172:173], off
	s_add_i32 m0, s98, 1024
	s_nop 0
	global_load_lds_dwordx4 v[174:175], off
	s_add_i32 m0, s98, 2048
	s_nop 0
	global_load_lds_dwordx4 v[176:177], off
	s_add_i32 m0, s98, 3072
	s_nop 0
	global_load_lds_dwordx4 v[178:179], off
	s_add_i32 m0, s98, 4096
	s_nop 0
	global_load_lds_dwordx4 v[180:181], off
	s_add_i32 m0, s98, 5120
	s_nop 0
	global_load_lds_dwordx4 v[182:183], off
	s_add_i32 m0, s98, 6144
	s_nop 0
	global_load_lds_dwordx4 v[184:185], off
	s_add_i32 m0, s98, 7168
	s_nop 0
	global_load_lds_dwordx4 v[186:187], off
	v_cmp_lt_i32_e32 vcc, 0, v100
	v_add_u32_e32 v100, -1, v100
	s_nop 0
	s_cbranch_vccz .Lsb_nostep_a
	v_lshl_add_u64 v[172:173], v[172:173], 0, v[188:189]
	v_lshl_add_u64 v[174:175], v[174:175], 0, v[188:189]
	v_lshl_add_u64 v[176:177], v[176:177], 0, v[188:189]
	v_lshl_add_u64 v[178:179], v[178:179], 0, v[188:189]
	v_lshl_add_u64 v[180:181], v[180:181], 0, v[190:191]
	v_lshl_add_u64 v[182:183], v[182:183], 0, v[190:191]
	v_lshl_add_u64 v[184:185], v[184:185], 0, v[190:191]
	v_lshl_add_u64 v[186:187], v[186:187], 0, v[190:191]
